# v62 but P4 outputs stored write-back (plain) with buffer_wbl2 kept at seam 4
# baseline (speedup 1.0000x reference)
.LBB0_351:
	global_load_dword v162, v1, s[42:43]
	global_load_dword v163, v1, s[42:43] offset:4
	v_add_u32_e32 v10, s15, v171
	v_ashrrev_i32_e32 v11, 31, v10
	s_mov_b64 s[68:69], 0x8000
	v_lshlrev_b64 v[154:155], 11, v[10:11]
	v_lshl_add_u64 v[154:155], v[4:5], 0, v[154:155]
	global_load_dwordx4 v[138:141], v[2:3], off
	global_load_dwordx4 v[74:77], v[154:155], off
	v_lshl_add_u64 v[156:157], v[154:155], 0, s[68:69]
	v_lshl_add_u64 v[158:159], v[156:157], 0, s[68:69]
	v_lshl_add_u64 v[160:161], v[158:159], 0, s[68:69]
	global_load_dwordx4 v[78:81], v[156:157], off
	global_load_dwordx4 v[82:85], v[158:159], off
	global_load_dwordx4 v[86:89], v[160:161], off
	global_load_dwordx4 v[142:145], v[2:3], off offset:64
	global_load_dwordx4 v[90:93], v[154:155], off offset:64
	global_load_dwordx4 v[94:97], v[156:157], off offset:64
	global_load_dwordx4 v[98:101], v[158:159], off offset:64
	global_load_dwordx4 v[102:105], v[160:161], off offset:64
	global_load_dwordx4 v[146:149], v[2:3], off offset:128
	global_load_dwordx4 v[106:109], v[154:155], off offset:128
	global_load_dwordx4 v[110:113], v[156:157], off offset:128
	global_load_dwordx4 v[114:117], v[158:159], off offset:128
	global_load_dwordx4 v[118:121], v[160:161], off offset:128
	global_load_dwordx4 v[150:153], v[2:3], off offset:192
	global_load_dwordx4 v[122:125], v[154:155], off offset:192
	global_load_dwordx4 v[126:129], v[156:157], off offset:192
	global_load_dwordx4 v[130:133], v[158:159], off offset:192
	global_load_dwordx4 v[134:137], v[160:161], off offset:192
	v_add_u32_e32 v10, s15, v204
	v_ashrrev_i32_e32 v11, 31, v10
	v_lshlrev_b64 v[50:51], 6, v[10:11]
	v_lshl_add_u64 v[66:67], s[60:61], 0, v[50:51]
	global_load_dwordx4 v[50:53], v[66:67], off
	global_load_dwordx4 v[54:57], v[66:67], off offset:16
	global_load_dwordx4 v[62:65], v[66:67], off offset:32
	global_load_dwordx4 v[58:61], v[66:67], off offset:48
	v_lshl_add_u64 v[10:11], v[10:11], 2, s[38:39]
	s_waitcnt vmcnt(22)
	v_mfma_f32_16x16x32_bf16 v[30:33], v[74:77], v[138:141], 0
	s_waitcnt vmcnt(21)
	v_mfma_f32_16x16x32_bf16 v[34:37], v[78:81], v[138:141], 0
	s_waitcnt vmcnt(20)
	v_mfma_f32_16x16x32_bf16 v[38:41], v[82:85], v[138:141], 0
	s_waitcnt vmcnt(19)
	v_mfma_f32_16x16x32_bf16 v[26:29], v[86:89], v[138:141], 0
	s_waitcnt vmcnt(17)
	v_mfma_f32_16x16x32_bf16 v[30:33], v[90:93], v[142:145], v[30:33]
	s_waitcnt vmcnt(16)
	v_mfma_f32_16x16x32_bf16 v[34:37], v[94:97], v[142:145], v[34:37]
	s_waitcnt vmcnt(15)
	v_mfma_f32_16x16x32_bf16 v[38:41], v[98:101], v[142:145], v[38:41]
	s_waitcnt vmcnt(14)
	v_mfma_f32_16x16x32_bf16 v[26:29], v[102:105], v[142:145], v[26:29]
	s_waitcnt vmcnt(12)
	v_mfma_f32_16x16x32_bf16 v[30:33], v[106:109], v[146:149], v[30:33]
	s_waitcnt vmcnt(11)
	v_mfma_f32_16x16x32_bf16 v[34:37], v[110:113], v[146:149], v[34:37]
	s_waitcnt vmcnt(10)
	v_mfma_f32_16x16x32_bf16 v[38:41], v[114:117], v[146:149], v[38:41]
	s_waitcnt vmcnt(9)
	v_mfma_f32_16x16x32_bf16 v[26:29], v[118:121], v[146:149], v[26:29]
	s_waitcnt vmcnt(7)
	v_mfma_f32_16x16x32_bf16 v[30:33], v[122:125], v[150:153], v[30:33]
	s_waitcnt vmcnt(6)
	v_mfma_f32_16x16x32_bf16 v[34:37], v[126:129], v[150:153], v[34:37]
	s_waitcnt vmcnt(5)
	v_mfma_f32_16x16x32_bf16 v[38:41], v[130:133], v[150:153], v[38:41]
	s_waitcnt vmcnt(4)
	v_mfma_f32_16x16x32_bf16 v[26:29], v[134:137], v[150:153], v[26:29]
	s_waitcnt vmcnt(0)
	v_add_f32_e32 v25, v50, v51
	s_nop 15
	s_nop 3
	ds_write2_b32 v19, v30, v31 offset1:16
	ds_write2_b32 v19, v32, v33 offset0:32 offset1:48
	s_nop 1
	ds_write2_b32 v22, v34, v35 offset1:16
	ds_write2_b32 v22, v36, v37 offset0:32 offset1:48
	s_nop 0
	ds_write2_b32 v23, v38, v39 offset1:16
	ds_write2_b32 v23, v40, v41 offset0:32 offset1:48
	ds_write2_b32 v24, v26, v27 offset1:16
	ds_write2_b32 v24, v28, v29 offset0:32 offset1:48
	s_waitcnt lgkmcnt(0)
	s_barrier
	v_mov_b32_e32 v34, v162
	v_add_f32_e32 v26, v52, v53
	v_add_f32_e32 v25, v25, v26
	s_waitcnt vmcnt(3)
	v_add_f32_e32 v27, v54, v55
	v_add_f32_e32 v28, v56, v57
	s_waitcnt vmcnt(2)
	v_add_f32_e32 v29, v62, v63
	v_add_f32_e32 v30, v64, v65
	v_add_f32_e32 v26, v27, v28
	s_waitcnt vmcnt(1)
	v_add_f32_e32 v31, v58, v59
	v_add_f32_e32 v32, v60, v61
	v_add_f32_e32 v27, v29, v30
	v_add_f32_e32 v25, v25, v26
	v_add_f32_e32 v28, v31, v32
	v_add_f32_e32 v25, v25, v27
	v_add_f32_e32 v25, v25, v28
	v_fmamk_f32 v25, v25, 0x3a800000, v20
	v_mul_f32_e32 v26, 0x4f800000, v25
	v_cmp_gt_f32_e32 vcc, s57, v25
	s_nop 1
	v_cndmask_b32_e32 v25, v25, v26, vcc
	v_sqrt_f32_e32 v26, v25
	s_nop 0
	v_add_u32_e32 v27, -1, v26
	v_add_u32_e32 v28, 1, v26
	v_fma_f32 v29, -v27, v26, v25
	v_fma_f32 v30, -v28, v26, v25
	v_cmp_ge_f32_e64 s[22:23], 0, v29
	s_nop 1
	v_cndmask_b32_e64 v26, v26, v27, s[22:23]
	v_cmp_lt_f32_e64 s[22:23], 0, v30
	s_nop 1
	v_cndmask_b32_e64 v26, v26, v28, s[22:23]
	v_mul_f32_e32 v27, 0x37800000, v26
	v_cndmask_b32_e32 v26, v26, v27, vcc
	v_cmp_class_f32_e32 vcc, v25, v21
	s_nop 1
	v_cndmask_b32_e32 v25, v26, v25, vcc
	v_div_scale_f32 v35, s[22:23], v25, v25, 1.0
	v_rcp_f32_e32 v37, v35
	ds_read2st64_b32 v[26:27], v12 offset1:16
	ds_read2st64_b32 v[28:29], v12 offset0:32 offset1:48
	ds_read2st64_b32 v[30:31], v12 offset0:64 offset1:80
	ds_read2st64_b32 v[32:33], v12 offset0:96 offset1:112
	v_div_scale_f32 v36, vcc, 1.0, v25, 1.0
	v_fma_f32 v38, -v35, v37, 1.0
	s_waitcnt lgkmcnt(3)
	v_add_f32_e32 v26, 0, v26
	v_fmac_f32_e32 v37, v38, v37
	v_add_f32_e32 v26, v26, v27
	v_mul_f32_e32 v38, v36, v37
	s_waitcnt lgkmcnt(2)
	v_add_f32_e32 v26, v26, v28
	v_fma_f32 v39, -v35, v38, v36
	v_add_f32_e32 v26, v26, v29
	v_fmac_f32_e32 v38, v39, v37
	s_waitcnt lgkmcnt(1)
	v_add_f32_e32 v26, v26, v30
	v_fma_f32 v27, -v35, v38, v36
	v_add_f32_e32 v26, v26, v31
	v_div_fmas_f32 v27, v27, v37, v38
	s_waitcnt lgkmcnt(0)
	v_add_f32_e32 v26, v26, v32
	v_div_fixup_f32 v25, v27, v25, 1.0
	v_add_f32_e32 v26, v26, v33
	s_waitcnt vmcnt(0)
	v_fmac_f32_e32 v34, v25, v26
	v_mul_f32_e64 v26, |v34|, s64
	v_exp_f32_e32 v26, v26
	v_min_f32_e32 v27, 0, v34
	v_lshl_add_u64 v[28:29], v[10:11], 0, s[46:47]
	v_add_f32_e32 v26, 1.0, v26
	v_log_f32_e32 v26, v26
	s_nop 0
	v_fmac_f32_e32 v27, 0xbf317218, v26
	s_nop 1
	v_add_f32_dpp v27, v27, v27 row_shr:1 row_mask:0xf bank_mask:0xf
	s_nop 1
	v_add_f32_dpp v27, v27, v27 row_shr:2 row_mask:0xf bank_mask:0xf
	s_nop 1
	v_add_f32_dpp v27, v27, v27 row_shr:4 row_mask:0xf bank_mask:0xf
	s_nop 1
	v_add_f32_dpp v27, v27, v27 row_shr:8 row_mask:0xf bank_mask:0xf
	s_nop 1
	v_add_f32_dpp v27, v27, v27 row_bcast:15 row_mask:0xa bank_mask:0xf
	s_nop 1
	v_add_f32_dpp v27, v27, v27 row_bcast:31 row_mask:0xc bank_mask:0xf
	v_mov_b32_e32 v26, v27
	global_store_dword v[28:29], v27, off
	s_and_saveexec_b64 s[22:23], s[0:1]
	s_cbranch_execz .LBB0_353
	s_add_i32 s44, s14, s65
	s_ashr_i32 s45, s44, 31
	s_lshl_b64 s[44:45], s[44:45], 2
	s_add_u32 s44, s74, s44
	s_addc_u32 s45, s75, s45
	global_store_dword v1, v26, s[44:45]
.LBB0_353:
	s_or_b64 exec, exec, s[22:23]
	v_mov_b32_e32 v34, v163
	v_add_u32_e32 v32, 4, v12
	ds_read2st64_b32 v[26:27], v32 offset1:16
	ds_read2st64_b32 v[28:29], v32 offset0:32 offset1:48
	ds_read2st64_b32 v[30:31], v32 offset0:64 offset1:80
	ds_read2st64_b32 v[32:33], v32 offset0:96 offset1:112
	v_lshl_add_u64 v[10:11], v[10:11], 0, s[48:49]
	s_waitcnt lgkmcnt(3)
	v_add_f32_e32 v26, 0, v26
	v_add_f32_e32 v26, v26, v27
	s_waitcnt lgkmcnt(2)
	v_add_f32_e32 v26, v26, v28
	v_add_f32_e32 v26, v26, v29
	s_waitcnt lgkmcnt(1)
	v_add_f32_e32 v26, v26, v30
	v_add_f32_e32 v26, v26, v31
	s_waitcnt lgkmcnt(0)
	v_add_f32_e32 v26, v26, v32
	v_add_f32_e32 v26, v26, v33
	v_fmac_f32_e32 v34, v25, v26
	v_mul_f32_e64 v25, |v34|, s64
	v_exp_f32_e32 v25, v25
	v_min_f32_e32 v26, 0, v34
	v_add_f32_e32 v25, 1.0, v25
	v_log_f32_e32 v25, v25
	s_nop 0
	v_fmac_f32_e32 v26, 0xbf317218, v25
	s_nop 1
	v_add_f32_dpp v26, v26, v26 row_shr:1 row_mask:0xf bank_mask:0xf
	s_nop 1
	v_add_f32_dpp v26, v26, v26 row_shr:2 row_mask:0xf bank_mask:0xf
	s_nop 1
	v_add_f32_dpp v26, v26, v26 row_shr:4 row_mask:0xf bank_mask:0xf
	s_nop 1
	v_add_f32_dpp v26, v26, v26 row_shr:8 row_mask:0xf bank_mask:0xf
	s_nop 1
	v_add_f32_dpp v26, v26, v26 row_bcast:15 row_mask:0xa bank_mask:0xf
	s_nop 1
	v_add_f32_dpp v26, v26, v26 row_bcast:31 row_mask:0xc bank_mask:0xf
	v_mov_b32_e32 v25, v26
	global_store_dword v[10:11], v26, off
	s_and_saveexec_b64 s[22:23], s[0:1]
	s_cbranch_execz .LBB0_350
	s_add_i32 s33, s14, s65
	s_add_i32 s44, s33, 0x100
	s_ashr_i32 s45, s44, 31
	s_lshl_b64 s[44:45], s[44:45], 2
	s_add_u32 s44, s74, s44
	s_addc_u32 s45, s75, s45
	global_store_dword v1, v25, s[44:45]
	s_branch .LBB0_350

.LBB0_443:
	global_load_dword v162, v1, s[40:41]
	global_load_dword v163, v1, s[40:41] offset:4
	v_add_u32_e32 v10, s15, v171
	v_ashrrev_i32_e32 v11, 31, v10
	s_mov_b64 s[68:69], 0x8000
	v_lshlrev_b64 v[154:155], 11, v[10:11]
	v_lshl_add_u64 v[154:155], v[4:5], 0, v[154:155]
	global_load_dwordx4 v[138:141], v[2:3], off
	global_load_dwordx4 v[74:77], v[154:155], off
	v_lshl_add_u64 v[156:157], v[154:155], 0, s[68:69]
	v_lshl_add_u64 v[158:159], v[156:157], 0, s[68:69]
	v_lshl_add_u64 v[160:161], v[158:159], 0, s[68:69]
	global_load_dwordx4 v[78:81], v[156:157], off
	global_load_dwordx4 v[82:85], v[158:159], off
	global_load_dwordx4 v[86:89], v[160:161], off
	global_load_dwordx4 v[142:145], v[2:3], off offset:64
	global_load_dwordx4 v[90:93], v[154:155], off offset:64
	global_load_dwordx4 v[94:97], v[156:157], off offset:64
	global_load_dwordx4 v[98:101], v[158:159], off offset:64
	global_load_dwordx4 v[102:105], v[160:161], off offset:64
	global_load_dwordx4 v[146:149], v[2:3], off offset:128
	global_load_dwordx4 v[106:109], v[154:155], off offset:128
	global_load_dwordx4 v[110:113], v[156:157], off offset:128
	global_load_dwordx4 v[114:117], v[158:159], off offset:128
	global_load_dwordx4 v[118:121], v[160:161], off offset:128
	global_load_dwordx4 v[150:153], v[2:3], off offset:192
	global_load_dwordx4 v[122:125], v[154:155], off offset:192
	global_load_dwordx4 v[126:129], v[156:157], off offset:192
	global_load_dwordx4 v[130:133], v[158:159], off offset:192
	global_load_dwordx4 v[134:137], v[160:161], off offset:192
	v_add_u32_e32 v10, s15, v204
	v_ashrrev_i32_e32 v11, 31, v10
	v_lshlrev_b64 v[50:51], 6, v[10:11]
	v_lshl_add_u64 v[66:67], s[60:61], 0, v[50:51]
	global_load_dwordx4 v[50:53], v[66:67], off
	global_load_dwordx4 v[54:57], v[66:67], off offset:16
	global_load_dwordx4 v[62:65], v[66:67], off offset:32
	global_load_dwordx4 v[58:61], v[66:67], off offset:48
	v_lshl_add_u64 v[10:11], v[10:11], 2, s[38:39]
	s_waitcnt vmcnt(22)
	v_mfma_f32_16x16x32_bf16 v[30:33], v[74:77], v[138:141], 0
	s_waitcnt vmcnt(21)
	v_mfma_f32_16x16x32_bf16 v[34:37], v[78:81], v[138:141], 0
	s_waitcnt vmcnt(20)
	v_mfma_f32_16x16x32_bf16 v[38:41], v[82:85], v[138:141], 0
	s_waitcnt vmcnt(19)
	v_mfma_f32_16x16x32_bf16 v[26:29], v[86:89], v[138:141], 0
	s_waitcnt vmcnt(17)
	v_mfma_f32_16x16x32_bf16 v[30:33], v[90:93], v[142:145], v[30:33]
	s_waitcnt vmcnt(16)
	v_mfma_f32_16x16x32_bf16 v[34:37], v[94:97], v[142:145], v[34:37]
	s_waitcnt vmcnt(15)
	v_mfma_f32_16x16x32_bf16 v[38:41], v[98:101], v[142:145], v[38:41]
	s_waitcnt vmcnt(14)
	v_mfma_f32_16x16x32_bf16 v[26:29], v[102:105], v[142:145], v[26:29]
	s_waitcnt vmcnt(12)
	v_mfma_f32_16x16x32_bf16 v[30:33], v[106:109], v[146:149], v[30:33]
	s_waitcnt vmcnt(11)
	v_mfma_f32_16x16x32_bf16 v[34:37], v[110:113], v[146:149], v[34:37]
	s_waitcnt vmcnt(10)
	v_mfma_f32_16x16x32_bf16 v[38:41], v[114:117], v[146:149], v[38:41]
	s_waitcnt vmcnt(9)
	v_mfma_f32_16x16x32_bf16 v[26:29], v[118:121], v[146:149], v[26:29]
	s_waitcnt vmcnt(7)
	v_mfma_f32_16x16x32_bf16 v[30:33], v[122:125], v[150:153], v[30:33]
	s_waitcnt vmcnt(6)
	v_mfma_f32_16x16x32_bf16 v[34:37], v[126:129], v[150:153], v[34:37]
	s_waitcnt vmcnt(5)
	v_mfma_f32_16x16x32_bf16 v[38:41], v[130:133], v[150:153], v[38:41]
	s_waitcnt vmcnt(4)
	v_mfma_f32_16x16x32_bf16 v[26:29], v[134:137], v[150:153], v[26:29]
	s_waitcnt vmcnt(0)
	v_add_f32_e32 v25, v50, v51
	s_nop 15
	s_nop 3
	ds_write2_b32 v19, v30, v31 offset1:16
	ds_write2_b32 v19, v32, v33 offset0:32 offset1:48
	s_nop 1
	ds_write2_b32 v22, v34, v35 offset1:16
	ds_write2_b32 v22, v36, v37 offset0:32 offset1:48
	s_nop 0
	ds_write2_b32 v23, v38, v39 offset1:16
	ds_write2_b32 v23, v40, v41 offset0:32 offset1:48
	ds_write2_b32 v24, v26, v27 offset1:16
	ds_write2_b32 v24, v28, v29 offset0:32 offset1:48
	s_waitcnt lgkmcnt(0)
	s_barrier
	v_mov_b32_e32 v34, v162
	v_add_f32_e32 v26, v52, v53
	v_add_f32_e32 v25, v25, v26
	s_waitcnt vmcnt(3)
	v_add_f32_e32 v27, v54, v55
	v_add_f32_e32 v28, v56, v57
	s_waitcnt vmcnt(2)
	v_add_f32_e32 v29, v62, v63
	v_add_f32_e32 v30, v64, v65
	v_add_f32_e32 v26, v27, v28
	s_waitcnt vmcnt(1)
	v_add_f32_e32 v31, v58, v59
	v_add_f32_e32 v32, v60, v61
	v_add_f32_e32 v27, v29, v30
	v_add_f32_e32 v25, v25, v26
	v_add_f32_e32 v28, v31, v32
	v_add_f32_e32 v25, v25, v27
	v_add_f32_e32 v25, v25, v28
	v_fmamk_f32 v25, v25, 0x3a800000, v20
	v_mul_f32_e32 v26, 0x4f800000, v25
	v_cmp_gt_f32_e32 vcc, s57, v25
	s_nop 1
	v_cndmask_b32_e32 v25, v25, v26, vcc
	v_sqrt_f32_e32 v26, v25
	s_nop 0
	v_add_u32_e32 v27, -1, v26
	v_add_u32_e32 v28, 1, v26
	v_fma_f32 v29, -v27, v26, v25
	v_fma_f32 v30, -v28, v26, v25
	v_cmp_ge_f32_e64 s[22:23], 0, v29
	s_nop 1
	v_cndmask_b32_e64 v26, v26, v27, s[22:23]
	v_cmp_lt_f32_e64 s[22:23], 0, v30
	s_nop 1
	v_cndmask_b32_e64 v26, v26, v28, s[22:23]
	v_mul_f32_e32 v27, 0x37800000, v26
	v_cndmask_b32_e32 v26, v26, v27, vcc
	v_cmp_class_f32_e32 vcc, v25, v21
	s_nop 1
	v_cndmask_b32_e32 v25, v26, v25, vcc
	v_div_scale_f32 v35, s[22:23], v25, v25, 1.0
	v_rcp_f32_e32 v37, v35
	ds_read2st64_b32 v[26:27], v12 offset1:16
	ds_read2st64_b32 v[28:29], v12 offset0:32 offset1:48
	ds_read2st64_b32 v[30:31], v12 offset0:64 offset1:80
	ds_read2st64_b32 v[32:33], v12 offset0:96 offset1:112
	v_div_scale_f32 v36, vcc, 1.0, v25, 1.0
	v_fma_f32 v38, -v35, v37, 1.0
	s_waitcnt lgkmcnt(3)
	v_add_f32_e32 v26, 0, v26
	v_fmac_f32_e32 v37, v38, v37
	v_add_f32_e32 v26, v26, v27
	v_mul_f32_e32 v38, v36, v37
	s_waitcnt lgkmcnt(2)
	v_add_f32_e32 v26, v26, v28
	v_fma_f32 v39, -v35, v38, v36
	v_add_f32_e32 v26, v26, v29
	v_fmac_f32_e32 v38, v39, v37
	s_waitcnt lgkmcnt(1)
	v_add_f32_e32 v26, v26, v30
	v_fma_f32 v27, -v35, v38, v36
	v_add_f32_e32 v26, v26, v31
	v_div_fmas_f32 v27, v27, v37, v38
	s_waitcnt lgkmcnt(0)
	v_add_f32_e32 v26, v26, v32
	v_div_fixup_f32 v25, v27, v25, 1.0
	v_add_f32_e32 v26, v26, v33
	s_waitcnt vmcnt(0)
	v_fmac_f32_e32 v34, v25, v26
	v_mul_f32_e64 v26, |v34|, s64
	v_exp_f32_e32 v26, v26
	v_min_f32_e32 v27, 0, v34
	v_lshl_add_u64 v[28:29], v[10:11], 0, s[58:59]
	v_add_f32_e32 v26, 1.0, v26
	v_log_f32_e32 v26, v26
	s_nop 0
	v_fmac_f32_e32 v27, 0xbf317218, v26
	s_nop 1
	v_add_f32_dpp v27, v27, v27 row_shr:1 row_mask:0xf bank_mask:0xf
	s_nop 1
	v_add_f32_dpp v27, v27, v27 row_shr:2 row_mask:0xf bank_mask:0xf
	s_nop 1
	v_add_f32_dpp v27, v27, v27 row_shr:4 row_mask:0xf bank_mask:0xf
	s_nop 1
	v_add_f32_dpp v27, v27, v27 row_shr:8 row_mask:0xf bank_mask:0xf
	s_nop 1
	v_add_f32_dpp v27, v27, v27 row_bcast:15 row_mask:0xa bank_mask:0xf
	s_nop 1
	v_add_f32_dpp v27, v27, v27 row_bcast:31 row_mask:0xc bank_mask:0xf
	v_mov_b32_e32 v26, v27
	global_store_dword v[28:29], v27, off
	s_and_saveexec_b64 s[22:23], s[0:1]
	s_cbranch_execz .LBB0_445
	s_add_i32 s66, s14, s65
	s_ashr_i32 s67, s66, 31
	s_lshl_b64 s[66:67], s[66:67], 2
	s_add_u32 s66, s74, s66
	s_addc_u32 s67, s75, s67
	global_store_dword v1, v26, s[66:67]
.LBB0_445:
	s_or_b64 exec, exec, s[22:23]
	v_mov_b32_e32 v34, v163
	v_add_u32_e32 v32, 4, v12
	ds_read2st64_b32 v[26:27], v32 offset1:16
	ds_read2st64_b32 v[28:29], v32 offset0:32 offset1:48
	ds_read2st64_b32 v[30:31], v32 offset0:64 offset1:80
	ds_read2st64_b32 v[32:33], v32 offset0:96 offset1:112
	v_lshl_add_u64 v[10:11], v[10:11], 0, s[62:63]
	s_waitcnt lgkmcnt(3)
	v_add_f32_e32 v26, 0, v26
	v_add_f32_e32 v26, v26, v27
	s_waitcnt lgkmcnt(2)
	v_add_f32_e32 v26, v26, v28
	v_add_f32_e32 v26, v26, v29
	s_waitcnt lgkmcnt(1)
	v_add_f32_e32 v26, v26, v30
	v_add_f32_e32 v26, v26, v31
	s_waitcnt lgkmcnt(0)
	v_add_f32_e32 v26, v26, v32
	v_add_f32_e32 v26, v26, v33
	v_fmac_f32_e32 v34, v25, v26
	v_mul_f32_e64 v25, |v34|, s64
	v_exp_f32_e32 v25, v25
	v_min_f32_e32 v26, 0, v34
	v_add_f32_e32 v25, 1.0, v25
	v_log_f32_e32 v25, v25
	s_nop 0
	v_fmac_f32_e32 v26, 0xbf317218, v25
	s_nop 1
	v_add_f32_dpp v26, v26, v26 row_shr:1 row_mask:0xf bank_mask:0xf
	s_nop 1
	v_add_f32_dpp v26, v26, v26 row_shr:2 row_mask:0xf bank_mask:0xf
	s_nop 1
	v_add_f32_dpp v26, v26, v26 row_shr:4 row_mask:0xf bank_mask:0xf
	s_nop 1
	v_add_f32_dpp v26, v26, v26 row_shr:8 row_mask:0xf bank_mask:0xf
	s_nop 1
	v_add_f32_dpp v26, v26, v26 row_bcast:15 row_mask:0xa bank_mask:0xf
	s_nop 1
	v_add_f32_dpp v26, v26, v26 row_bcast:31 row_mask:0xc bank_mask:0xf
	v_mov_b32_e32 v25, v26
	global_store_dword v[10:11], v26, off
	s_and_saveexec_b64 s[22:23], s[0:1]
	s_cbranch_execz .LBB0_442
	s_add_i32 s33, s14, s65
	s_add_i32 s66, s33, 0x100
	s_ashr_i32 s67, s66, 31
	s_lshl_b64 s[66:67], s[66:67], 2
	s_add_u32 s66, s74, s66
	s_addc_u32 s67, s75, s67
	global_store_dword v1, v25, s[66:67]
	s_branch .LBB0_442

.LBB0_486:
	s_or_b64 exec, exec, s[20:21]
	v_cvt_f32_u32_e32 v7, v3
	s_waitcnt vmcnt(0)
	v_readfirstlane_b32 s14, v6
	v_sub_u32_e32 v6, 0, v3
	v_rcp_iflag_f32_e32 v7, v7
	v_add_u32_e32 v8, s14, v1
	v_mul_f32_e32 v7, 0x4f7ffffe, v7
	v_cvt_u32_f32_e32 v7, v7
	v_mul_lo_u32 v1, v6, v7
	v_mul_hi_u32 v1, v7, v1
	v_add_u32_e32 v1, v7, v1
	v_mul_hi_u32 v1, v8, v1
	v_mul_lo_u32 v6, v1, v3
	v_sub_u32_e32 v6, v8, v6
	v_add_u32_e32 v7, 1, v1
	v_cmp_ge_u32_e32 vcc, v6, v3
	s_nop 1
	v_cndmask_b32_e32 v1, v1, v7, vcc
	v_sub_u32_e32 v7, v6, v3
	v_cndmask_b32_e32 v6, v6, v7, vcc
	v_add_u32_e32 v7, 1, v1
	v_cmp_ge_u32_e32 vcc, v6, v3
	v_add_u32_e32 v6, 1, v8
	s_nop 0
	v_cndmask_b32_e32 v1, v1, v7, vcc
	v_mul_lo_u32 v7, v3, v1
	v_add_u32_e32 v3, v7, v3
	v_cmp_ne_u32_e32 vcc, v6, v3
	s_cbranch_vccnz .Lmy_ft4_nl
	buffer_wbl2 sc1
	s_waitcnt vmcnt(0) lgkmcnt(0)
	v_mov_b32_e32 v6, 0x3000
	v_mov_b32_e32 v7, 1
	global_atomic_add v6, v7, s[52:53] offset:1024
